# even-layer LRU conv: the three history-row loads per output issued at the top of the iteration with counted waits (no per-tap global round trip)
# baseline (speedup 1.0000x reference)
.LBB0_1113:
	v_ashrrev_i32_e32 v64, 6, v74
	s_movk_i32 s0, 0x3fff
	v_cmp_gt_i32_e64 s[6:7], s33, v64
	v_cmp_lt_i32_e64 s[8:9], s0, v64
	s_and_saveexec_b64 s[4:5], s[8:9]
	s_xor_b64 s[20:21], exec, s[4:5]
	v_add_u32_e32 v0, 0xffffc000, v64
	v_bfe_u32 v58, v74, 6, 3
	v_lshrrev_b32_e32 v60, 3, v0
	s_or_saveexec_b64 s[20:21], s[20:21]
	v_mov_b32_e32 v76, 5
	s_xor_b64 exec, exec, s[20:21]
	v_bfe_u32 v58, v74, 6, 11
	v_ashrrev_i32_e32 v60, 17, v74
	v_mov_b32_e32 v76, 0x7fd
	s_or_b64 exec, exec, s[20:21]
	v_and_b32_e32 v2, 0x1f8, v75
	v_lshlrev_b32_e32 v0, 2, v2
	v_lshlrev_b32_e32 v92, 1, v2
	v_mov_b32_e32 v93, v1
	v_add_u32_e32 v94, -3, v64
	v_mov_b64_e32 v[80:81], s[50:51]
	v_mad_i64_i32 v[80:81], s[4:5], v94, s82, v[80:81]
	v_lshl_add_u64 v[80:81], v[80:81], 0, v[92:93]
	v_add_co_u32_e32 v80, vcc, 0x14712000, v80
	s_nop 1
	v_addc_co_u32_e32 v81, vcc, 0, v81, vcc
	global_load_dwordx4 v[80:83], v[80:81], off offset:1024
	v_add_u32_e32 v94, -2, v64
	v_mov_b64_e32 v[84:85], s[50:51]
	v_mad_i64_i32 v[84:85], s[4:5], v94, s82, v[84:85]
	v_lshl_add_u64 v[84:85], v[84:85], 0, v[92:93]
	v_add_co_u32_e32 v84, vcc, 0x14712000, v84
	s_nop 1
	v_addc_co_u32_e32 v85, vcc, 0, v85, vcc
	global_load_dwordx4 v[84:87], v[84:85], off offset:1024
	v_add_u32_e32 v94, -1, v64
	v_mov_b64_e32 v[88:89], s[50:51]
	v_mad_i64_i32 v[88:89], s[4:5], v94, s82, v[88:89]
	v_lshl_add_u64 v[88:89], v[88:89], 0, v[92:93]
	v_add_co_u32_e32 v88, vcc, 0x14712000, v88
	s_nop 1
	v_addc_co_u32_e32 v89, vcc, 0, v89, vcc
	global_load_dwordx4 v[88:91], v[88:89], off offset:1024
	global_load_dwordx4 v[18:21], v0, s[12:13] offset:16
	global_load_dwordx4 v[22:25], v0, s[12:13]
	v_ashrrev_i32_e32 v61, 31, v60
	v_lshl_add_u64 v[68:69], s[14:15], 0, v[60:61]
	v_readlane_b32 s0, v254, 60
	v_mad_u64_u32 v[62:63], s[4:5], v68, 3, 0
	v_readlane_b32 s1, v254, 61
	s_load_dwordx2 s[4:5], s[0:1], 0x20
	v_mad_i32_i24 v63, v69, 3, v63
	v_cmp_gt_u32_e32 vcc, 3, v58
	s_waitcnt lgkmcnt(0)
	v_lshl_add_u64 v[70:71], s[4:5], 0, v[0:1]
	s_and_saveexec_b64 s[4:5], vcc
	s_xor_b64 s[20:21], exec, s[4:5]
	s_cbranch_execz .LBB0_1121
	v_mov_b32_e32 v29, 0
	v_mov_b32_e32 v28, 0
	v_mov_b32_e32 v27, 0
	v_mov_b32_e32 v26, 0
	v_mov_b32_e32 v33, 0
	v_mov_b32_e32 v32, 0
	v_mov_b32_e32 v31, 0
	v_mov_b32_e32 v30, 0
	s_and_saveexec_b64 s[22:23], s[8:9]
	s_cbranch_execz .LBB0_1120
	v_mov_b32_e32 v59, v1
	v_lshl_add_u64 v[4:5], v[62:63], 0, v[58:59]
	v_lshlrev_b64 v[4:5], 11, v[4:5]
	v_lshl_add_u64 v[4:5], v[70:71], 0, v[4:5]
	global_load_dwordx4 v[30:33], v[4:5], off
	global_load_dwordx4 v[26:29], v[4:5], off offset:16

.LBB0_1121:
	s_or_saveexec_b64 s[20:21], s[20:21]
	v_lshlrev_b32_e32 v66, 1, v2
	s_xor_b64 exec, exec, s[20:21]
	s_cbranch_execz .LBB0_1123
	s_waitcnt vmcnt(4)
	v_mov_b32_e32 v67, v1
	v_mov_b32_e32 v2, v80
	v_mov_b32_e32 v3, v81
	v_mov_b32_e32 v4, v82
	v_mov_b32_e32 v5, v83
	v_lshlrev_b32_e32 v30, 16, v2
	v_and_b32_e32 v31, 0xffff0000, v2
	v_lshlrev_b32_e32 v32, 16, v3
	v_and_b32_e32 v33, 0xffff0000, v3
	v_lshlrev_b32_e32 v26, 16, v4
	v_and_b32_e32 v27, 0xffff0000, v4
	v_lshlrev_b32_e32 v28, 16, v5
	v_and_b32_e32 v29, 0xffff0000, v5

.LBB0_1127:
	s_andn2_saveexec_b64 s[20:21], s[20:21]
	s_cbranch_execz .LBB0_1129
	s_waitcnt vmcnt(5)
	v_mov_b32_e32 v67, v1
	v_mov_b32_e32 v2, v84
	v_mov_b32_e32 v3, v85
	v_mov_b32_e32 v4, v86
	v_mov_b32_e32 v5, v87
	v_lshlrev_b32_e32 v46, 16, v2
	v_and_b32_e32 v47, 0xffff0000, v2
	v_lshlrev_b32_e32 v48, 16, v3
	v_and_b32_e32 v49, 0xffff0000, v3
	v_lshlrev_b32_e32 v42, 16, v4
	v_and_b32_e32 v43, 0xffff0000, v4
	v_lshlrev_b32_e32 v44, 16, v5
	v_and_b32_e32 v45, 0xffff0000, v5
.LBB0_1129:
	s_or_b64 exec, exec, s[20:21]
	v_lshl_add_u64 v[72:73], s[10:11], 0, v[0:1]
	global_load_dwordx4 v[50:53], v[72:73], off offset:2064
	global_load_dwordx4 v[54:57], v[72:73], off offset:2048
	v_cmp_ne_u32_e32 vcc, 0, v58
	s_and_saveexec_b64 s[4:5], vcc
	s_xor_b64 s[20:21], exec, s[4:5]
	s_cbranch_execz .LBB0_1131
	s_waitcnt vmcnt(6)
	v_mov_b32_e32 v67, v1
	v_mov_b32_e32 v2, v88
	v_mov_b32_e32 v3, v89
	v_mov_b32_e32 v4, v90
	v_mov_b32_e32 v5, v91
	v_lshlrev_b32_e32 v10, 16, v2
	v_and_b32_e32 v14, 0xffff0000, v2
	v_lshlrev_b32_e32 v12, 16, v3
	v_and_b32_e32 v16, 0xffff0000, v3
	v_lshlrev_b32_e32 v2, 16, v4
	v_and_b32_e32 v6, 0xffff0000, v4
	v_lshlrev_b32_e32 v4, 16, v5
	v_and_b32_e32 v8, 0xffff0000, v5
